# PanelRms step 4: issue the 8 agent-scope partial loads together instead of one round trip each
# baseline (speedup 1.0000x reference)
.LBB0_568:
	v_readlane_b32 s4, v254, 54
	s_waitcnt vmcnt(0) lgkmcnt(0)
	s_barrier
	s_nop 0
	v_mov_b32_e32 v3, s4
	ds_read_b32 v180, v3
	s_and_saveexec_b64 s[10:11], s[8:9]
	s_cbranch_execz .LBB0_570
	v_lshlrev_b64 v[0:1], 5, v[0:1]
	v_lshl_add_u64 v[0:1], s[14:15], 0, v[0:1]
	global_load_dword v3, v[0:1], off sc1
	global_load_dword v4, v[0:1], off offset:4 sc1
	global_load_dword v5, v[0:1], off offset:8 sc1
	global_load_dword v6, v[0:1], off offset:12 sc1
	global_load_dword v7, v[0:1], off offset:16 sc1
	global_load_dword v8, v[0:1], off offset:20 sc1
	global_load_dword v9, v[0:1], off offset:24 sc1
	global_load_dword v10, v[0:1], off offset:28 sc1
	s_mov_b32 s4, 0xf800000
	s_waitcnt vmcnt(7)
	v_add_f32_e32 v3, 0, v3
	s_waitcnt vmcnt(6)
	v_add_f32_e32 v3, v3, v4
	s_waitcnt vmcnt(5)
	v_add_f32_e32 v3, v3, v5
	s_waitcnt vmcnt(4)
	v_add_f32_e32 v3, v3, v6
	s_waitcnt vmcnt(3)
	v_add_f32_e32 v3, v3, v7
	s_waitcnt vmcnt(2)
	v_add_f32_e32 v3, v3, v8
	s_waitcnt vmcnt(1)
	v_add_f32_e32 v3, v3, v9
	s_waitcnt vmcnt(0)
	v_add_f32_e32 v0, v3, v10
	v_fmamk_f32 v0, v0, 0x3a000000, v198
	v_cmp_gt_f32_e32 vcc, s4, v0
	v_mul_f32_e32 v1, 0x4f800000, v0
	s_nop 0
	v_cndmask_b32_e32 v0, v0, v1, vcc
	v_sqrt_f32_e32 v1, v0
	s_nop 0
	v_add_u32_e32 v3, -1, v1
	v_fma_f32 v4, -v3, v1, v0
	v_cmp_ge_f32_e64 s[8:9], 0, v4
	v_add_u32_e32 v4, 1, v1
	s_nop 0
	v_cndmask_b32_e64 v3, v1, v3, s[8:9]
	v_fma_f32 v1, -v4, v1, v0
	v_cmp_lt_f32_e64 s[8:9], 0, v1
	s_nop 1
	v_cndmask_b32_e64 v1, v3, v4, s[8:9]
	v_mul_f32_e32 v3, 0x37800000, v1
	v_cndmask_b32_e32 v1, v1, v3, vcc
	v_cmp_class_f32_e32 vcc, v0, v199
	s_nop 1
	v_cndmask_b32_e32 v0, v1, v0, vcc
	v_div_scale_f32 v1, s[4:5], v0, v0, 1.0
	v_rcp_f32_e32 v3, v1
	s_nop 0
	v_fma_f32 v4, -v1, v3, 1.0
	v_fmac_f32_e32 v3, v4, v3
	v_div_scale_f32 v4, vcc, 1.0, v0, 1.0
	v_mul_f32_e32 v5, v4, v3
	v_fma_f32 v6, -v1, v5, v4
	v_fmac_f32_e32 v5, v6, v3
	v_fma_f32 v1, -v1, v5, v4
	v_div_fmas_f32 v1, v1, v3, v5
	v_div_fixup_f32 v0, v1, v0, 1.0
	v_lshl_add_u32 v1, v2, 2, 0
	v_add_u32_e32 v1, 0x21000, v1
	ds_write_b32 v1, v0

.LBB0_1091:
	v_readlane_b32 s4, v254, 54
	s_waitcnt vmcnt(0) lgkmcnt(0)
	s_barrier
	s_nop 0
	v_mov_b32_e32 v3, s4
	ds_read_b32 v180, v3
	s_and_saveexec_b64 s[10:11], s[8:9]
	v_readlane_b32 s85, v255, 11
	v_readlane_b32 s84, v255, 12
	s_cbranch_execz .LBB0_1093
	v_lshlrev_b64 v[0:1], 5, v[0:1]
	v_lshl_add_u64 v[0:1], s[14:15], 0, v[0:1]
	global_load_dword v3, v[0:1], off sc1
	global_load_dword v4, v[0:1], off offset:4 sc1
	global_load_dword v5, v[0:1], off offset:8 sc1
	global_load_dword v6, v[0:1], off offset:12 sc1
	global_load_dword v7, v[0:1], off offset:16 sc1
	global_load_dword v8, v[0:1], off offset:20 sc1
	global_load_dword v9, v[0:1], off offset:24 sc1
	global_load_dword v10, v[0:1], off offset:28 sc1
	s_mov_b32 s4, 0xf800000
	s_waitcnt vmcnt(7)
	v_add_f32_e32 v3, 0, v3
	s_waitcnt vmcnt(6)
	v_add_f32_e32 v3, v3, v4
	s_waitcnt vmcnt(5)
	v_add_f32_e32 v3, v3, v5
	s_waitcnt vmcnt(4)
	v_add_f32_e32 v3, v3, v6
	s_waitcnt vmcnt(3)
	v_add_f32_e32 v3, v3, v7
	s_waitcnt vmcnt(2)
	v_add_f32_e32 v3, v3, v8
	s_waitcnt vmcnt(1)
	v_add_f32_e32 v3, v3, v9
	s_waitcnt vmcnt(0)
	v_add_f32_e32 v0, v3, v10
	v_fmamk_f32 v0, v0, 0x3a000000, v198
	v_cmp_gt_f32_e32 vcc, s4, v0
	v_mul_f32_e32 v1, 0x4f800000, v0
	s_nop 0
	v_cndmask_b32_e32 v0, v0, v1, vcc
	v_sqrt_f32_e32 v1, v0
	s_nop 0
	v_add_u32_e32 v3, -1, v1
	v_fma_f32 v4, -v3, v1, v0
	v_cmp_ge_f32_e64 s[8:9], 0, v4
	v_add_u32_e32 v4, 1, v1
	s_nop 0
	v_cndmask_b32_e64 v3, v1, v3, s[8:9]
	v_fma_f32 v1, -v4, v1, v0
	v_cmp_lt_f32_e64 s[8:9], 0, v1
	s_nop 1
	v_cndmask_b32_e64 v1, v3, v4, s[8:9]
	v_mul_f32_e32 v3, 0x37800000, v1
	v_cndmask_b32_e32 v1, v1, v3, vcc
	v_cmp_class_f32_e32 vcc, v0, v199
	s_nop 1
	v_cndmask_b32_e32 v0, v1, v0, vcc
	v_div_scale_f32 v1, s[4:5], v0, v0, 1.0
	v_rcp_f32_e32 v3, v1
	s_nop 0
	v_fma_f32 v4, -v1, v3, 1.0
	v_fmac_f32_e32 v3, v4, v3
	v_div_scale_f32 v4, vcc, 1.0, v0, 1.0
	v_mul_f32_e32 v5, v4, v3
	v_fma_f32 v6, -v1, v5, v4
	v_fmac_f32_e32 v5, v6, v3
	v_fma_f32 v1, -v1, v5, v4
	v_div_fmas_f32 v1, v1, v3, v5
	v_div_fixup_f32 v0, v1, v0, 1.0
	v_lshl_add_u32 v1, v2, 2, 0
	v_add_u32_e32 v1, 0x21000, v1
	ds_write_b32 v1, v0

.LBB0_1467:
	v_readlane_b32 s4, v254, 54
	s_waitcnt vmcnt(0) lgkmcnt(0)
	s_barrier
	s_nop 0
	v_mov_b32_e32 v3, s4
	ds_read_b32 v165, v3
	s_and_saveexec_b64 s[14:15], s[12:13]
	s_cbranch_execz .LBB0_1469
	v_lshlrev_b64 v[0:1], 5, v[0:1]
	v_lshl_add_u64 v[0:1], s[34:35], 0, v[0:1]
	global_load_dword v3, v[0:1], off sc1
	global_load_dword v4, v[0:1], off offset:4 sc1
	global_load_dword v5, v[0:1], off offset:8 sc1
	global_load_dword v6, v[0:1], off offset:12 sc1
	global_load_dword v7, v[0:1], off offset:16 sc1
	global_load_dword v8, v[0:1], off offset:20 sc1
	global_load_dword v9, v[0:1], off offset:24 sc1
	global_load_dword v10, v[0:1], off offset:28 sc1
	s_mov_b32 s4, 0xf800000
	s_waitcnt vmcnt(7)
	v_add_f32_e32 v3, 0, v3
	s_waitcnt vmcnt(6)
	v_add_f32_e32 v3, v3, v4
	s_waitcnt vmcnt(5)
	v_add_f32_e32 v3, v3, v5
	s_waitcnt vmcnt(4)
	v_add_f32_e32 v3, v3, v6
	s_waitcnt vmcnt(3)
	v_add_f32_e32 v3, v3, v7
	s_waitcnt vmcnt(2)
	v_add_f32_e32 v3, v3, v8
	s_waitcnt vmcnt(1)
	v_add_f32_e32 v3, v3, v9
	s_waitcnt vmcnt(0)
	v_add_f32_e32 v0, v3, v10
	v_fmamk_f32 v0, v0, 0x3a000000, v198
	v_cmp_gt_f32_e32 vcc, s4, v0
	v_mul_f32_e32 v1, 0x4f800000, v0
	s_nop 0
	v_cndmask_b32_e32 v0, v0, v1, vcc
	v_sqrt_f32_e32 v1, v0
	s_nop 0
	v_add_u32_e32 v3, -1, v1
	v_fma_f32 v4, -v3, v1, v0
	v_cmp_ge_f32_e64 s[12:13], 0, v4
	v_add_u32_e32 v4, 1, v1
	s_nop 0
	v_cndmask_b32_e64 v3, v1, v3, s[12:13]
	v_fma_f32 v1, -v4, v1, v0
	v_cmp_lt_f32_e64 s[12:13], 0, v1
	s_nop 1
	v_cndmask_b32_e64 v1, v3, v4, s[12:13]
	v_mul_f32_e32 v3, 0x37800000, v1
	v_cndmask_b32_e32 v1, v1, v3, vcc
	v_cmp_class_f32_e32 vcc, v0, v199
	s_nop 1
	v_cndmask_b32_e32 v0, v1, v0, vcc
	v_div_scale_f32 v1, s[4:5], v0, v0, 1.0
	v_rcp_f32_e32 v3, v1
	s_nop 0
	v_fma_f32 v4, -v1, v3, 1.0
	v_fmac_f32_e32 v3, v4, v3
	v_div_scale_f32 v4, vcc, 1.0, v0, 1.0
	v_mul_f32_e32 v5, v4, v3
	v_fma_f32 v6, -v1, v5, v4
	v_fmac_f32_e32 v5, v6, v3
	v_fma_f32 v1, -v1, v5, v4
	v_div_fmas_f32 v1, v1, v3, v5
	v_div_fixup_f32 v0, v1, v0, 1.0
	v_lshl_add_u32 v1, v2, 2, 0
	v_add_u32_e32 v1, 0x21000, v1
	ds_write_b32 v1, v0
